# mixer to mixer-out grid barrier as one posted atomic on 32 spread counters plus a 32-lane poll (flat barrier) instead of the two-level XCD protocol
# baseline (speedup 1.0000x reference)
.LBB0_263:
	s_mul_i32 s3, s29, s28
	s_ashr_i32 s29, s28, 31
	s_mov_b64 s[4:5], 0xe900100
	s_cmpk_eq_i32 s28, 0x100
	v_writelane_b32 v255, s4, 1
	s_mul_i32 s3, s3, s2
	s_cselect_b64 s[92:93], -1, 0
	v_writelane_b32 v255, s5, 2
	s_add_i32 s2, 0, 0x23f00
	v_writelane_b32 v255, s2, 3
	s_add_i32 s2, 0, 0x23f04
	v_writelane_b32 v255, s2, 4
	s_add_i32 s2, 0, 0x23f10
	s_ashr_i32 s83, s82, 31
	v_writelane_b32 v255, s2, 5
	s_lshl_b64 s[84:85], s[82:83], 11
	s_lshl_b64 s[34:35], s[82:83], 12
	v_writelane_b32 v255, s82, 6
	v_mbcnt_lo_u32_b32 v0, -1, 0
	v_mbcnt_hi_u32_b32 v182, -1, v0
	v_writelane_b32 v255, s83, 7
	v_writelane_b32 v255, s84, 8
	s_mov_b32 s39, 0
	v_and_b32_e32 v0, 64, v182
	v_writelane_b32 v255, s85, 9
	v_writelane_b32 v255, s92, 10
	v_writelane_b32 v255, s39, 45
	v_writelane_b32 v255, s39, 46
	v_writelane_b32 v255, s39, 47
	v_writelane_b32 v255, s39, 48
	v_writelane_b32 v255, s39, 49
	v_mov_b32_e32 v145, 0
	s_movk_i32 s67, 0x1000
	s_movk_i32 s69, 0xfff
	s_mov_b32 s73, 0xff000000
	s_mov_b64 s[94:95], 0x1000
	v_mov_b32_e32 v146, 0x358637bd
	s_mov_b32 s72, 0x800000
	s_mov_b32 s74, 0xf7800000
	s_movk_i32 s75, 0x1fff
	v_mov_b32_e32 v185, 0x1000
	v_mov_b32_e32 v186, 0x2000
	v_mov_b32_e32 v189, 1
	s_mov_b32 s76, 0x10000
	s_mov_b32 s77, 0x18000
	s_mov_b64 s[48:49], 0x80
	s_mov_b32 s86, 0x8000
	s_movk_i32 s68, 0x1600
	s_mov_b32 s87, 0x40000
	s_mov_b32 s90, 0x48000
	s_mov_b32 s78, 0x50000
	s_mov_b32 s79, 0x58000
	s_mov_b32 s52, 0x3e000000
	s_mov_b32 s66, 0x3c800000
	s_add_i32 s80, 0, 0x43c
	s_add_i32 s81, 0, 60
	v_add_u32_e32 v183, 64, v0
	v_xor_b32_e32 v188, 1, v182
	v_xor_b32_e32 v254, 2, v182
	v_xor_b32_e32 v187, 16, v182
	v_xor_b32_e32 v184, 32, v182
	v_mov_b64_e32 v[148:149], 0x2bf
	v_mov_b64_e32 v[150:151], 0x100
	v_mov_b64_e32 v[152:153], 0xff
	v_mov_b32_e32 v194, 0xcf
	v_mov_b32_e32 v195, 0x3cf
	v_mov_b32_e32 v196, 0xdf
	v_mov_b32_e32 v197, 0x3df
	v_mov_b32_e32 v198, 0xef
	v_mov_b32_e32 v199, 0x3ef
	v_mov_b32_e32 v200, 0xff
	v_mov_b32_e32 v201, 0x3ff
	v_mov_b32_e32 v202, 0xf149f2ca
	s_mov_b32 s70, s39
	v_writelane_b32 v255, s93, 11
	s_branch .LBB0_265

.Lxb_noinv_6:
	v_cmp_eq_u32_e32 vcc, 0, v0
	s_and_saveexec_b64 s[4:5], vcc
	s_cbranch_execz .LBB0_1145
	s_load_dwordx2 s[34:35], s[8:9], 0x98
	v_readlane_b32 s14, v255, 0
	v_readlane_b32 s15, v255, 49
	s_nop 0
	s_and_b32 s14, s14, 31
	s_lshl_b32 s14, s14, 7
	s_add_u32 s14, s14, 0xe000
	s_add_u32 s15, s15, 8
	v_writelane_b32 v255, s15, 49
	v_mov_b32_e32 v0, s14
	s_waitcnt lgkmcnt(0)
	global_atomic_add v0, v189, s[34:35]
	s_mov_b32 exec_lo, -1
	s_mov_b32 exec_hi, 0
	v_mbcnt_lo_u32_b32 v7, -1, 0
	v_lshlrev_b32_e32 v7, 7, v7
	v_add_u32_e32 v7, 0xe000, v7
	s_mov_b32 s32, 0
.Lfb32_poll_b6:
	global_load_dword v6, v7, s[34:35] sc1
	s_waitcnt vmcnt(0)
	v_cmp_le_u32_e32 vcc, s15, v6
	s_nop 1
	s_cmp_eq_u32 vcc_lo, -1
	s_cbranch_scc1 .Lfb32_done_b6
	s_sleep 1
	s_add_u32 s32, s32, 1
	s_cmp_lt_u32 s32, 0x2000
	s_cbranch_scc1 .Lfb32_poll_b6
